# diff-attention prompt loop: cross-row max via v_permlane16/32_swap instead of two ds_bpermute round trips, and seven V^T fragments read from LDS ahead of the softmax (was two)
# baseline (speedup 1.0000x reference)
.LBB0_1082:
	ds_read_b128 v[112:115], v124
	ds_read_b128 v[116:119], v124 offset:64
	ds_read_b128 v[120:123], v124 offset:128
	ds_read_b128 v[166:169], v124 offset:192
	ds_read_b128 v[170:173], v147 offset:8448
	ds_read_b128 v[174:177], v147 offset:8512
	ds_read_b128 v[178:181], v147 offset:8576
	ds_read_b128 v[182:185], v147 offset:8640
	s_add_i32 s29, s29, 1
	s_waitcnt lgkmcnt(7)
	v_mfma_f32_16x16x32_bf16 v[112:115], v[112:115], v[0:3], 0
	s_waitcnt lgkmcnt(6)
	v_mfma_f32_16x16x32_bf16 v[112:115], v[116:119], v[4:7], v[112:115]
	s_waitcnt lgkmcnt(5)
	v_mfma_f32_16x16x32_bf16 v[112:115], v[120:123], v[8:11], v[112:115]
	s_waitcnt lgkmcnt(4)
	v_mfma_f32_16x16x32_bf16 v[166:169], v[166:169], v[12:15], v[112:115]
	s_nop 5
	ds_read_b128 v[112:115], v147 offset:16896
	ds_read_b128 v[116:119], v147 offset:16960
	ds_read_b128 v[186:189], v147 offset:17024
	ds_read_b128 v[190:193], v147 offset:17088
	s_waitcnt lgkmcnt(7)
	v_mfma_f32_16x16x32_bf16 v[120:123], v[170:173], v[0:3], 0
	s_waitcnt lgkmcnt(6)
	v_mfma_f32_16x16x32_bf16 v[120:123], v[174:177], v[4:7], v[120:123]
	s_waitcnt lgkmcnt(5)
	v_mfma_f32_16x16x32_bf16 v[120:123], v[178:181], v[8:11], v[120:123]
	s_waitcnt lgkmcnt(4)
	v_mfma_f32_16x16x32_bf16 v[120:123], v[182:185], v[12:15], v[120:123]
	ds_read_b128 v[170:173], v148
	ds_read_b128 v[174:177], v148 offset:64
	ds_read_b128 v[178:181], v148 offset:128
	ds_read_b128 v[182:185], v148 offset:192
	s_waitcnt lgkmcnt(7)
	v_mfma_f32_16x16x32_bf16 v[112:115], v[112:115], v[0:3], 0
	s_waitcnt lgkmcnt(6)
	v_mfma_f32_16x16x32_bf16 v[112:115], v[116:119], v[4:7], v[112:115]
	s_waitcnt lgkmcnt(5)
	v_mfma_f32_16x16x32_bf16 v[112:115], v[186:189], v[8:11], v[112:115]
	s_waitcnt lgkmcnt(4)
	v_mfma_f32_16x16x32_bf16 v[116:119], v[190:193], v[12:15], v[112:115]
	s_waitcnt lgkmcnt(3)
	v_mfma_f32_16x16x32_bf16 v[112:115], v[170:173], v[0:3], 0
	s_waitcnt lgkmcnt(2)
	v_mfma_f32_16x16x32_bf16 v[112:115], v[174:177], v[4:7], v[112:115]
	s_waitcnt lgkmcnt(1)
	v_mfma_f32_16x16x32_bf16 v[112:115], v[178:181], v[8:11], v[112:115]
	s_waitcnt lgkmcnt(0)
	v_mfma_f32_16x16x32_bf16 v[112:115], v[182:185], v[12:15], v[112:115]
	ds_read_b128 v[232:235], v143 offset:0
	ds_read_b128 v[236:239], v143 offset:2560
	ds_read_b128 v[240:243], v143 offset:5120
	ds_read_b128 v[244:247], v143 offset:7680
	ds_read_b128 v[248:251], v143 offset:10240
	ds_read_b128 v[186:189], v143 offset:15360
	ds_read_b128 v[190:193], v143 offset:17920
	s_mov_b32 s26, 0xff800000
	v_sub_f32_e32 v156, v156, v220
	v_fma_f32 v170, v166, v126, -v204
	v_fma_f32 v171, v167, v126, -v205
	v_fma_f32 v172, v168, v126, -v206
	v_fma_f32 v173, v169, v126, -v207
	v_fma_f32 v174, v120, v126, -v208
	v_fma_f32 v175, v121, v126, -v209
	v_fma_f32 v176, v122, v126, -v210
	v_fma_f32 v177, v123, v126, -v211
	v_fma_f32 v178, v116, v126, -v212
	v_fma_f32 v179, v117, v126, -v213
	v_fma_f32 v180, v118, v126, -v214
	v_fma_f32 v181, v119, v126, -v215
	v_fma_f32 v182, v112, v126, -v216
	v_fma_f32 v183, v113, v126, -v217
	v_fma_f32 v184, v114, v126, -v218
	v_fma_f32 v185, v115, v126, -v219
	v_max3_f32 v112, v170, v171, v172
	v_max3_f32 v112, v112, v173, v174
	v_max3_f32 v112, v112, v175, v176
	v_max3_f32 v112, v112, v177, v178
	v_max3_f32 v112, v112, v179, v180
	v_max3_f32 v112, v112, v181, v182
	v_max3_f32 v112, v112, v183, v184
	v_max_f32_e32 v112, v112, v185
	v_mov_b32_e32 v115, v112
	v_mov_b32_e32 v114, v112
	s_nop 1
	v_permlane16_swap_b32_e32 v115, v114
	v_max_f32_e32 v112, v115, v114
	v_mov_b32_e32 v115, v112
	v_mov_b32_e32 v114, v112
	s_nop 1
	v_permlane32_swap_b32_e32 v115, v114
	v_max3_f32 v112, v156, v115, v114
	v_sub_f32_e32 v115, v156, v112
	v_sub_f32_e32 v170, v170, v112
	v_exp_f32_e32 v170, v170
	v_sub_f32_e32 v171, v171, v112
	v_exp_f32_e32 v118, v115
	v_exp_f32_e32 v171, v171
	v_sub_f32_e32 v172, v172, v112
	v_exp_f32_e32 v172, v172
	v_sub_f32_e32 v173, v173, v112
	v_exp_f32_e32 v173, v173
	v_sub_f32_e32 v174, v174, v112
	v_exp_f32_e32 v174, v174
	v_sub_f32_e32 v175, v175, v112
	v_exp_f32_e32 v175, v175
	v_sub_f32_e32 v176, v176, v112
	v_exp_f32_e32 v176, v176
	v_sub_f32_e32 v177, v177, v112
	v_exp_f32_e32 v177, v177
	v_sub_f32_e32 v178, v178, v112
	v_exp_f32_e32 v178, v178
	v_sub_f32_e32 v179, v179, v112
	v_exp_f32_e32 v179, v179
	v_sub_f32_e32 v180, v180, v112
	v_exp_f32_e32 v180, v180
	v_sub_f32_e32 v181, v181, v112
	v_exp_f32_e32 v181, v181
	v_sub_f32_e32 v182, v182, v112
	v_exp_f32_e32 v182, v182
	v_sub_f32_e32 v183, v183, v112
	v_exp_f32_e32 v183, v183
	v_sub_f32_e32 v184, v184, v112
	v_exp_f32_e32 v184, v184
	v_sub_f32_e32 v185, v185, v112
	v_exp_f32_e32 v185, v185
	v_add_f32_e32 v113, v170, v171
	v_add_f32_e32 v113, v113, v172
	v_add_f32_e32 v113, v113, v173
	v_add_f32_e32 v113, v113, v174
	v_add_f32_e32 v113, v113, v175
	v_add_f32_e32 v113, v113, v176
	v_add_f32_e32 v113, v113, v177
	v_add_f32_e32 v113, v113, v178
	v_add_f32_e32 v113, v113, v179
	v_add_f32_e32 v113, v113, v180
	v_add_f32_e32 v113, v113, v181
	v_add_f32_e32 v113, v113, v182
	v_add_f32_e32 v113, v113, v183
	v_add_f32_e32 v113, v113, v184
	v_add_f32_e32 v113, v113, v185
	v_fmac_f32_e32 v113, v155, v118
	v_pk_mul_f32 v[110:111], v[110:111], v[118:119] op_sel_hi:[1,0]
	v_pk_mul_f32 v[108:109], v[108:109], v[118:119] op_sel_hi:[1,0]
	v_pk_mul_f32 v[106:107], v[106:107], v[118:119] op_sel_hi:[1,0]
	v_pk_mul_f32 v[104:105], v[104:105], v[118:119] op_sel_hi:[1,0]
	v_pk_mul_f32 v[102:103], v[102:103], v[118:119] op_sel_hi:[1,0]
	v_pk_mul_f32 v[100:101], v[100:101], v[118:119] op_sel_hi:[1,0]
	v_pk_mul_f32 v[116:117], v[94:95], v[118:119] op_sel_hi:[1,0]
	v_pk_mul_f32 v[114:115], v[92:93], v[118:119] op_sel_hi:[1,0]
	v_pk_mul_f32 v[94:95], v[98:99], v[118:119] op_sel_hi:[1,0]
	v_pk_mul_f32 v[92:93], v[96:97], v[118:119] op_sel_hi:[1,0]
	v_pk_mul_f32 v[90:91], v[90:91], v[118:119] op_sel_hi:[1,0]
	v_pk_mul_f32 v[88:89], v[88:89], v[118:119] op_sel_hi:[1,0]
	v_pk_mul_f32 v[86:87], v[86:87], v[118:119] op_sel_hi:[1,0]
	v_pk_mul_f32 v[84:85], v[84:85], v[118:119] op_sel_hi:[1,0]
	v_pk_mul_f32 v[82:83], v[82:83], v[118:119] op_sel_hi:[1,0]
	v_pk_mul_f32 v[80:81], v[80:81], v[118:119] op_sel_hi:[1,0]
	v_pk_mul_f32 v[78:79], v[78:79], v[118:119] op_sel_hi:[1,0]
	v_pk_mul_f32 v[76:77], v[76:77], v[118:119] op_sel_hi:[1,0]
	v_pk_mul_f32 v[74:75], v[74:75], v[118:119] op_sel_hi:[1,0]
	v_pk_mul_f32 v[72:73], v[72:73], v[118:119] op_sel_hi:[1,0]
	v_pk_mul_f32 v[70:71], v[70:71], v[118:119] op_sel_hi:[1,0]
	v_pk_mul_f32 v[68:69], v[68:69], v[118:119] op_sel_hi:[1,0]
	v_pk_mul_f32 v[66:67], v[66:67], v[118:119] op_sel_hi:[1,0]
	v_pk_mul_f32 v[64:65], v[64:65], v[118:119] op_sel_hi:[1,0]
	v_pk_mul_f32 v[62:63], v[62:63], v[118:119] op_sel_hi:[1,0]
	v_pk_mul_f32 v[60:61], v[60:61], v[118:119] op_sel_hi:[1,0]
	v_pk_mul_f32 v[58:59], v[58:59], v[118:119] op_sel_hi:[1,0]
	v_pk_mul_f32 v[56:57], v[56:57], v[118:119] op_sel_hi:[1,0]
	v_pk_mul_f32 v[54:55], v[54:55], v[118:119] op_sel_hi:[1,0]
	v_pk_mul_f32 v[52:53], v[52:53], v[118:119] op_sel_hi:[1,0]
	v_pk_mul_f32 v[98:99], v[50:51], v[118:119] op_sel_hi:[1,0]
	v_pk_mul_f32 v[96:97], v[48:49], v[118:119] op_sel_hi:[1,0]
	v_cvt_pk_bf16_f32 v118, v170, v171
	v_cvt_pk_bf16_f32 v119, v172, v173
	v_cvt_pk_bf16_f32 v120, v174, v175
	v_cvt_pk_bf16_f32 v121, v176, v177
	v_cvt_pk_bf16_f32 v48, v178, v179
	v_cvt_pk_bf16_f32 v49, v180, v181
	v_cvt_pk_bf16_f32 v50, v182, v183
	v_cvt_pk_bf16_f32 v51, v184, v185
	ds_read_b128 v[182:185], v143 offset:12800
	s_waitcnt lgkmcnt(7)
	v_mfma_f32_16x16x32_bf16 v[108:111], v[232:235], v[118:121], v[108:111]
	s_waitcnt lgkmcnt(6)
	v_mfma_f32_16x16x32_bf16 v[104:107], v[236:239], v[118:121], v[104:107]
	s_waitcnt lgkmcnt(5)
	v_mfma_f32_16x16x32_bf16 v[100:103], v[240:243], v[118:121], v[100:103]
	s_waitcnt lgkmcnt(4)
	v_mfma_f32_16x16x32_bf16 v[114:117], v[244:247], v[118:121], v[114:117]
	ds_read_b128 v[156:159], v143 offset:20480
	ds_read_b128 v[166:169], v143 offset:23040
	ds_read_b128 v[170:173], v143 offset:25600
	ds_read_b128 v[174:177], v143 offset:28160
	s_waitcnt lgkmcnt(4)
	v_mfma_f32_16x16x32_bf16 v[88:91], v[182:185], v[118:121], v[88:91]
	v_mfma_f32_16x16x32_bf16 v[84:87], v[186:189], v[118:121], v[84:87]
	v_mfma_f32_16x16x32_bf16 v[80:83], v[190:193], v[118:121], v[80:83]
	v_mfma_f32_16x16x32_bf16 v[178:181], v[248:251], v[118:121], v[92:95]
	s_nop 2
	ds_read_b128 v[92:95], v143 offset:30720
	ds_read_b128 v[182:185], v143 offset:33280
	ds_read_b128 v[186:189], v143 offset:35840
	ds_read_b128 v[190:193], v143 offset:38400
	s_waitcnt lgkmcnt(7)
	v_mfma_f32_16x16x32_bf16 v[76:79], v[156:159], v[118:121], v[76:79]
	s_waitcnt lgkmcnt(6)
	v_mfma_f32_16x16x32_bf16 v[72:75], v[166:169], v[118:121], v[72:75]
	s_waitcnt lgkmcnt(5)
	v_mfma_f32_16x16x32_bf16 v[68:71], v[170:173], v[118:121], v[68:71]
	s_waitcnt lgkmcnt(4)
	v_mfma_f32_16x16x32_bf16 v[64:67], v[174:177], v[118:121], v[64:67]
	ds_read_b128 v[156:159], v143 offset:64
	ds_read_b128 v[166:169], v143 offset:2624
	ds_read_b128 v[170:173], v143 offset:5184
	ds_read_b128 v[174:177], v143 offset:7744
	s_waitcnt lgkmcnt(7)
	v_mfma_f32_16x16x32_bf16 v[60:63], v[92:95], v[118:121], v[60:63]
	s_waitcnt lgkmcnt(6)
	v_mfma_f32_16x16x32_bf16 v[56:59], v[182:185], v[118:121], v[56:59]
	s_waitcnt lgkmcnt(5)
	v_mfma_f32_16x16x32_bf16 v[52:55], v[186:189], v[118:121], v[52:55]
	s_waitcnt lgkmcnt(4)
	v_mfma_f32_16x16x32_bf16 v[118:121], v[190:193], v[118:121], v[96:99]
	s_nop 2
	ds_read_b128 v[96:99], v143 offset:10304
	ds_read_b128 v[182:185], v143 offset:12864
	ds_read_b128 v[186:189], v143 offset:15424
	ds_read_b128 v[190:193], v143 offset:17984
	s_waitcnt lgkmcnt(7)
	v_mfma_f32_16x16x32_bf16 v[108:111], v[156:159], v[48:51], v[108:111]
	s_waitcnt lgkmcnt(6)
	v_mfma_f32_16x16x32_bf16 v[104:107], v[166:169], v[48:51], v[104:107]
	s_waitcnt lgkmcnt(5)
	v_mfma_f32_16x16x32_bf16 v[100:103], v[170:173], v[48:51], v[100:103]
	s_waitcnt lgkmcnt(4)
	v_mfma_f32_16x16x32_bf16 v[92:95], v[174:177], v[48:51], v[114:117]
	s_nop 2
	ds_read_b128 v[114:117], v143 offset:20544
	ds_read_b128 v[156:159], v143 offset:23104
	ds_read_b128 v[166:169], v143 offset:25664
	ds_read_b128 v[170:173], v143 offset:28224
	s_waitcnt lgkmcnt(7)
	v_mfma_f32_16x16x32_bf16 v[96:99], v[96:99], v[48:51], v[178:181]
	s_waitcnt lgkmcnt(6)
	v_mfma_f32_16x16x32_bf16 v[88:91], v[182:185], v[48:51], v[88:91]
	s_waitcnt lgkmcnt(5)
	v_mfma_f32_16x16x32_bf16 v[84:87], v[186:189], v[48:51], v[84:87]
	s_waitcnt lgkmcnt(4)
	v_mfma_f32_16x16x32_bf16 v[80:83], v[190:193], v[48:51], v[80:83]
	ds_read_b128 v[174:177], v143 offset:30784
	ds_read_b128 v[178:181], v143 offset:33344
	ds_read_b128 v[182:185], v143 offset:35904
	ds_read_b128 v[186:189], v143 offset:38464
	s_waitcnt lgkmcnt(7)
	v_mfma_f32_16x16x32_bf16 v[76:79], v[114:117], v[48:51], v[76:79]
	s_waitcnt lgkmcnt(6)
	v_mfma_f32_16x16x32_bf16 v[72:75], v[156:159], v[48:51], v[72:75]
	s_waitcnt lgkmcnt(5)
	v_mfma_f32_16x16x32_bf16 v[68:71], v[166:169], v[48:51], v[68:71]
	s_waitcnt lgkmcnt(4)
	v_mfma_f32_16x16x32_bf16 v[64:67], v[170:173], v[48:51], v[64:67]
	s_waitcnt lgkmcnt(3)
	v_mfma_f32_16x16x32_bf16 v[60:63], v[174:177], v[48:51], v[60:63]
	s_waitcnt lgkmcnt(2)
	v_mfma_f32_16x16x32_bf16 v[56:59], v[178:181], v[48:51], v[56:59]
	s_waitcnt lgkmcnt(1)
	v_mfma_f32_16x16x32_bf16 v[52:55], v[182:185], v[48:51], v[52:55]
	s_waitcnt lgkmcnt(0)
	v_mfma_f32_16x16x32_bf16 v[48:51], v[186:189], v[48:51], v[118:121]
	s_mov_b64 s[34:35], 0x80
	v_lshl_add_u64 v[132:133], v[132:133], 0, s[34:35]
	s_mov_b64 s[34:35], 0x40000
	v_subrev_u32_e32 v144, 64, v144
	s_cmp_eq_u32 s30, s29
	v_lshl_add_u64 v[136:137], v[136:137], 0, s[34:35]
	s_cbranch_scc1 .LBB0_1084
	v_mov_b32_e32 v155, v113
	v_mov_b32_e32 v156, v112
	s_branch .LBB0_1080
